# scan helpers: v98 trims + key L2-norm inverse via v_rsq_f32(max(ss,1e-24)) (f32; 35 fewer helper instructions per half-chunk)
# speedup vs baseline: 1.0042x; 1.0042x over previous
; __device__ __forceinline__ float sigm(float x) { return __builtin_amdgcn_rcpf(1.f + __expf(-x)); }
; template <int CTRL> __device__ __forceinline__ float dppf(float x) { return __builtin_bit_cast(float, __builtin_amdgcn_update_dpp(0, __builtin_bit_cast(int, x), CTRL, 0xF, 0xF, false)); }
; __device__ __forceinline__ void phase_rwkv_scan(const Fr& F, int jr) {
;     ...
;                     Wv[pp * 64 + hk] = __expf(-0.60653066f * sigm(w0v[hh] + cw[reg]));
;                     Av[pp * 64 + hk] = sigm(a0v[hh] + ca[reg]); }
;     ...
;                 ss += dppf<0xB1>(ss); ss += dppf<0x4E>(ss); ss += dppf<0x141>(ss); bon += dppf<0xB1>(bon); bon += dppf<0x4E>(bon); bon += dppf<0x141>(bon);
;                 if (s == 0 && half == 0 && j8 == 0) Bon[((size_t)b * TB + tokof(s, chunk * 64 + p2)) * 16 + h] = bon;
;                 const float inv = 1.f / fmaxf(sqrtf(ss), 1e-12f);
.Lrw0_hnl0:
	v_mov_b32_e32 v196, v232
	s_nop 1
	v_permlane16_swap_b32_e32 v232, v196
	s_nop 1
	v_add_f32_e32 v232, v232, v196
	v_mov_b32_e32 v196, v232
	s_nop 1
	v_permlane32_swap_b32_e32 v232, v196
	s_nop 1
	v_add_f32_e32 v232, v232, v196
	v_max_f32_e32 v196, 0x179abe15, v232
	v_rsq_f32_e32 v232, v196
	v_pk_mul_f32 v[136:137], v[136:137], v[122:123]
	v_pk_mul_f32 v[138:139], v[138:139], v[122:123]
	v_pk_mul_f32 v[144:145], v[144:145], v[122:123]
	v_pk_mul_f32 v[146:147], v[146:147], v[122:123]
	v_pk_mul_f32 v[140:141], v[140:141], v[122:123]
	v_pk_mul_f32 v[142:143], v[142:143], v[122:123]
	v_pk_mul_f32 v[148:149], v[148:149], v[122:123]
	v_pk_mul_f32 v[150:151], v[150:151], v[122:123]
	v_exp_f32_e32 v136, v136
	v_exp_f32_e32 v137, v137
	v_exp_f32_e32 v138, v138
	v_exp_f32_e32 v139, v139
	v_exp_f32_e32 v144, v144
	v_exp_f32_e32 v145, v145
	v_exp_f32_e32 v146, v146
	v_exp_f32_e32 v147, v147
	v_exp_f32_e32 v140, v140
	v_exp_f32_e32 v141, v141
	v_exp_f32_e32 v142, v142
	v_exp_f32_e32 v143, v143
	v_exp_f32_e32 v148, v148
	v_exp_f32_e32 v149, v149
	v_exp_f32_e32 v150, v150
	v_exp_f32_e32 v151, v151
	v_pk_add_f32 v[136:137], v[136:137], 1.0 op_sel_hi:[1,0]
	v_pk_add_f32 v[138:139], v[138:139], 1.0 op_sel_hi:[1,0]
	v_pk_add_f32 v[144:145], v[144:145], 1.0 op_sel_hi:[1,0]
	v_pk_add_f32 v[146:147], v[146:147], 1.0 op_sel_hi:[1,0]
	v_pk_add_f32 v[140:141], v[140:141], 1.0 op_sel_hi:[1,0]
	v_pk_add_f32 v[142:143], v[142:143], 1.0 op_sel_hi:[1,0]
	v_pk_add_f32 v[148:149], v[148:149], 1.0 op_sel_hi:[1,0]
	v_pk_add_f32 v[150:151], v[150:151], 1.0 op_sel_hi:[1,0]
	v_rcp_f32_e32 v136, v136
	v_rcp_f32_e32 v137, v137
	v_rcp_f32_e32 v138, v138
	v_rcp_f32_e32 v139, v139
	v_rcp_f32_e32 v144, v144
	v_rcp_f32_e32 v145, v145
	v_rcp_f32_e32 v146, v146
	v_rcp_f32_e32 v147, v147
	v_rcp_f32_e32 v140, v140
	v_rcp_f32_e32 v141, v141
	v_rcp_f32_e32 v142, v142
	v_rcp_f32_e32 v143, v143
	v_rcp_f32_e32 v148, v148
	v_rcp_f32_e32 v149, v149
	v_rcp_f32_e32 v150, v150
	v_rcp_f32_e32 v151, v151
	v_pk_mul_f32 v[236:237], v[136:137], v[124:125]
	v_pk_mul_f32 v[238:239], v[138:139], v[124:125]
	v_pk_mul_f32 v[240:241], v[140:141], v[124:125]
	v_pk_mul_f32 v[242:243], v[142:143], v[124:125]
	v_pk_mul_f32 v[136:137], v[136:137], v[124:125]
	v_pk_mul_f32 v[138:139], v[138:139], v[124:125]
	v_pk_mul_f32 v[140:141], v[140:141], v[124:125]
	v_pk_mul_f32 v[142:143], v[142:143], v[124:125]
	v_add_f32_dpp v136, v136, v136 row_shr:1 row_mask:0xf bank_mask:0xf
	v_add_f32_dpp v137, v137, v137 row_shr:1 row_mask:0xf bank_mask:0xf
	v_add_f32_dpp v138, v138, v138 row_shr:1 row_mask:0xf bank_mask:0xf
	v_add_f32_dpp v139, v139, v139 row_shr:1 row_mask:0xf bank_mask:0xf
	v_add_f32_dpp v140, v140, v140 row_shr:1 row_mask:0xf bank_mask:0xf
	v_add_f32_dpp v141, v141, v141 row_shr:1 row_mask:0xf bank_mask:0xf
	v_add_f32_dpp v142, v142, v142 row_shr:1 row_mask:0xf bank_mask:0xf
	v_add_f32_dpp v143, v143, v143 row_shr:1 row_mask:0xf bank_mask:0xf
	v_add_f32_dpp v136, v136, v136 row_shr:2 row_mask:0xf bank_mask:0xf
	v_add_f32_dpp v137, v137, v137 row_shr:2 row_mask:0xf bank_mask:0xf
	v_add_f32_dpp v138, v138, v138 row_shr:2 row_mask:0xf bank_mask:0xf
	v_add_f32_dpp v139, v139, v139 row_shr:2 row_mask:0xf bank_mask:0xf
	v_add_f32_dpp v140, v140, v140 row_shr:2 row_mask:0xf bank_mask:0xf
	v_add_f32_dpp v141, v141, v141 row_shr:2 row_mask:0xf bank_mask:0xf
	v_add_f32_dpp v142, v142, v142 row_shr:2 row_mask:0xf bank_mask:0xf
	v_add_f32_dpp v143, v143, v143 row_shr:2 row_mask:0xf bank_mask:0xf
	v_add_f32_dpp v136, v136, v136 row_shr:4 row_mask:0xf bank_mask:0xf
	v_add_f32_dpp v137, v137, v137 row_shr:4 row_mask:0xf bank_mask:0xf
	v_add_f32_dpp v138, v138, v138 row_shr:4 row_mask:0xf bank_mask:0xf
	v_add_f32_dpp v139, v139, v139 row_shr:4 row_mask:0xf bank_mask:0xf
	v_add_f32_dpp v140, v140, v140 row_shr:4 row_mask:0xf bank_mask:0xf
	v_add_f32_dpp v141, v141, v141 row_shr:4 row_mask:0xf bank_mask:0xf
	v_add_f32_dpp v142, v142, v142 row_shr:4 row_mask:0xf bank_mask:0xf
	v_add_f32_dpp v143, v143, v143 row_shr:4 row_mask:0xf bank_mask:0xf
	v_add_f32_dpp v136, v136, v136 row_shr:8 row_mask:0xf bank_mask:0xf
	v_add_f32_dpp v137, v137, v137 row_shr:8 row_mask:0xf bank_mask:0xf
	v_add_f32_dpp v138, v138, v138 row_shr:8 row_mask:0xf bank_mask:0xf
	v_add_f32_dpp v139, v139, v139 row_shr:8 row_mask:0xf bank_mask:0xf
; __device__ __forceinline__ void phase_rwkv_scan(const Fr& F, int jr) {
;     ...
;                 if (s == 0 && half == 0 && j8 == 0) Bon[((size_t)b * TB + tokof(s, chunk * 64 + p2)) * 16 + h] = bon;
;                 const float inv = 1.f / fmaxf(sqrtf(ss), 1e-12f);
;                 const f32x4 av0 = *(const f32x4*)(Av + p2 * 64 + hk0), av1 = *(const f32x4*)(Av + p2 * 64 + hk0 + 4);
;                 const float av[8] = {av0.x, av0.y, av0.z, av0.w, av1.x, av1.y, av1.z, av1.w};
;                 float o1[8], o2[8], o3[8];
; #pragma unroll
;                 for (int i = 0; i < 8; ++i) { const float kkv = kq[i] * inv; o1[i] = kkv; o2[i] = kkv * av[i]; o3[i] = kr[i] * (1.f + (av[i] - 1.f) * kac[i]); }
;                 const int o = p2 * 64 + hk0;
;                 *(f32x4*)(KK + o) = (f32x4){o1[0], o1[1], o1[2], o1[3]}; *(f32x4*)(KK + o + 4) = (f32x4){o1[4], o1[5], o1[6], o1[7]};
;                 *(f32x4*)(Bv + o) = (f32x4){o2[0], o2[1], o2[2], o2[3]}; *(f32x4*)(Bv + o + 4) = (f32x4){o2[4], o2[5], o2[6], o2[7]};
;                 *(f32x4*)(KD + o) = (f32x4){o3[0], o3[1], o3[2], o3[3]}; *(f32x4*)(KD + o + 4) = (f32x4){o3[4], o3[5], o3[6], o3[7]};
;                 *(f32x4*)(Rr + o) = (f32x4){rr[0], rr[1], rr[2], rr[3]}; *(f32x4*)(Rr + o + 4) = (f32x4){rr[4], rr[5], rr[6], rr[7]};
;                 *(f32x4*)(Vv + p2 * 32 + 4 * j8) = (f32x4){lo_bf(vw.x), hi_bf(vw.x), lo_bf(vw.y), hi_bf(vw.y)};
	v_add_f32_dpp v140, v140, v140 row_shr:8 row_mask:0xf bank_mask:0xf
	v_add_f32_dpp v141, v141, v141 row_shr:8 row_mask:0xf bank_mask:0xf
	v_add_f32_dpp v142, v142, v142 row_shr:8 row_mask:0xf bank_mask:0xf
	v_add_f32_dpp v143, v143, v143 row_shr:8 row_mask:0xf bank_mask:0xf
	v_pk_add_f32 v[236:237], v[136:137], v[236:237] neg_lo:[0,1] neg_hi:[0,1]
	v_pk_add_f32 v[238:239], v[138:139], v[238:239] neg_lo:[0,1] neg_hi:[0,1]
	v_pk_add_f32 v[240:241], v[140:141], v[240:241] neg_lo:[0,1] neg_hi:[0,1]
	v_pk_add_f32 v[242:243], v[142:143], v[242:243] neg_lo:[0,1] neg_hi:[0,1]
	v_exp_f32_e64 v244, -v136
	v_exp_f32_e64 v245, -v137
	v_exp_f32_e64 v246, -v138
	v_exp_f32_e64 v247, -v139
	v_exp_f32_e64 v248, -v140
	v_exp_f32_e64 v249, -v141
	v_exp_f32_e64 v250, -v142
	v_exp_f32_e64 v251, -v143
	v_exp_f32_e32 v236, v236
	v_exp_f32_e32 v237, v237
	v_exp_f32_e32 v238, v238
	v_exp_f32_e32 v239, v239
	v_exp_f32_e32 v240, v240
	v_exp_f32_e32 v241, v241
	v_exp_f32_e32 v242, v242
	v_exp_f32_e32 v243, v243
	v_exp_f32_e32 v136, v136
	v_exp_f32_e32 v137, v137
	v_exp_f32_e32 v138, v138
	v_exp_f32_e32 v139, v139
	v_exp_f32_e32 v140, v140
	v_exp_f32_e32 v141, v141
	v_exp_f32_e32 v142, v142
	v_exp_f32_e32 v143, v143
	v_pk_mul_f32 v[204:205], v[176:177], v[232:233] op_sel_hi:[1,0]
	v_pk_mul_f32 v[206:207], v[178:179], v[232:233] op_sel_hi:[1,0]
	v_pk_add_f32 v[212:213], v[144:145], -1.0 op_sel_hi:[1,0]
	v_pk_add_f32 v[214:215], v[146:147], -1.0 op_sel_hi:[1,0]
	v_pk_mul_f32 v[208:209], v[204:205], v[144:145]
	v_pk_mul_f32 v[210:211], v[206:207], v[146:147]
	v_pk_fma_f32 v[212:213], v[64:65], v[212:213], 1.0 op_sel_hi:[1,1,0]
	v_pk_fma_f32 v[214:215], v[66:67], v[214:215], 1.0 op_sel_hi:[1,1,0]
	ds_write_b128 v224, v[136:139] offset:0
	v_pk_mul_f32 v[204:205], v[204:205], v[236:237]
	v_pk_mul_f32 v[206:207], v[206:207], v[238:239]
	v_pk_mul_f32 v[212:213], v[212:213], v[152:153]
	v_pk_mul_f32 v[214:215], v[214:215], v[154:155]
	ds_write_b128 v224, v[204:207] offset:8704
	v_pk_mul_f32 v[208:209], v[208:209], v[244:245]
	v_pk_mul_f32 v[210:211], v[210:211], v[246:247]
	v_pk_mul_f32 v[196:197], v[168:169], v[136:137]
	v_pk_mul_f32 v[198:199], v[170:171], v[138:139]
	ds_write_b128 v224, v[208:211] offset:17408
	v_pk_mul_f32 v[212:213], v[212:213], v[244:245]
	v_pk_mul_f32 v[214:215], v[214:215], v[246:247]
	ds_write_b128 v224, v[196:199] offset:34816
	ds_write_b128 v224, v[212:215] offset:26112
	v_pk_mul_f32 v[204:205], v[180:181], v[232:233] op_sel_hi:[1,0]
	v_pk_mul_f32 v[206:207], v[182:183], v[232:233] op_sel_hi:[1,0]
	v_pk_add_f32 v[212:213], v[148:149], -1.0 op_sel_hi:[1,0]
	v_pk_add_f32 v[214:215], v[150:151], -1.0 op_sel_hi:[1,0]
	v_pk_mul_f32 v[208:209], v[204:205], v[148:149]
	v_pk_mul_f32 v[210:211], v[206:207], v[150:151]
	v_pk_fma_f32 v[212:213], v[68:69], v[212:213], 1.0 op_sel_hi:[1,1,0]
	v_pk_fma_f32 v[214:215], v[70:71], v[214:215], 1.0 op_sel_hi:[1,1,0]
	ds_write_b128 v224, v[140:143] offset:64
	v_pk_mul_f32 v[204:205], v[204:205], v[240:241]
	v_pk_mul_f32 v[206:207], v[206:207], v[242:243]
	v_pk_mul_f32 v[212:213], v[212:213], v[156:157]
	v_pk_mul_f32 v[214:215], v[214:215], v[158:159]
	ds_write_b128 v224, v[204:207] offset:8768
	v_pk_mul_f32 v[208:209], v[208:209], v[248:249]
	v_pk_mul_f32 v[210:211], v[210:211], v[250:251]
	v_pk_mul_f32 v[196:197], v[172:173], v[140:141]
	v_pk_mul_f32 v[198:199], v[174:175], v[142:143]
	ds_write_b128 v224, v[208:211] offset:17472
	v_pk_mul_f32 v[212:213], v[212:213], v[248:249]
	v_pk_mul_f32 v[214:215], v[214:215], v[250:251]
	ds_write_b128 v224, v[196:199] offset:34880
	ds_write_b128 v224, v[212:215] offset:26176
	v_mov_b32_e32 v204, v193
	v_mov_b32_e32 v205, v192
	v_mov_b32_e32 v206, v195
	v_mov_b32_e32 v207, v194
	ds_write_b64 v225, v[192:193] offset:43520
	ds_write_b64 v225, v[204:205] offset:43536
	ds_write_b64 v225, v[194:195] offset:43552
	ds_write_b64 v225, v[206:207] offset:43568
	s_cmp_eq_u32 s32, 0
	s_cbranch_scc1 .Lrw0_hnb0
	v_mov_b32_e32 v196, v234
	s_nop 1
	v_permlane16_swap_b32_e32 v234, v196
	s_nop 1
	v_add_f32_e32 v234, v234, v196
	v_mov_b32_e32 v196, v234
	s_nop 1
	v_permlane32_swap_b32_e32 v234, v196
	s_nop 1
	v_add_f32_e32 v234, v234, v196
	v_cmp_gt_u32_e32 vcc, 16, v130
	s_and_saveexec_b64 s[56:57], vcc
	global_store_dword v202, v234, s[44:45]
	s_mov_b64 exec, s[56:57]
